# v60 + RWKV loop: waves 0-3 at priority 1 (wave 0 priority 3 during the solve interval)
# baseline (speedup 1.0000x reference)
; #define LAS __attribute__((address_space(3)))
; __device__ __forceinline__ void lds_barrier() { asm volatile("s_waitcnt lgkmcnt(0)" ::: "memory"); __builtin_amdgcn_s_barrier(); asm volatile("" ::: "memory"); }
; __device__ __forceinline__ void rwkv_chunk_item(const P& p, const Ctx& c, int seg, int w, bool save) {
;     ...
;     for (int ch = 0; ch < SEGT / 16; ++ch) {
;         const int pb = ch & 1;
;         int tidv = c.tid, l15 = l15c, quad = quadc; asm volatile("" : "+v"(tidv), "+v"(l15), "+v"(quad));
;         LAS bf16_t* EA = (LAS bf16_t*)(OB + pb * OPB + O_EA); LAS bf16_t* EBT = (LAS bf16_t*)(OB + pb * OPB + O_EBT); LAS bf16_t* UV = (LAS bf16_t*)(OB + pb * OPB + O_UV);
;         LAS bf16_t* MT1 = (LAS bf16_t*)(OB + pb * OPB + O_MT1); LAS bf16_t* NT = (LAS bf16_t*)(OB + pb * OPB + O_NT); LAS float* MABT = (LAS float*)(OB + pb * OPB + O_MABT); LAS float* GT = (LAS float*)(OB + pb * OPB + O_GT);
;         lds_barrier();
.LBB0_886:
	s_and_b64 vcc, exec, s[68:69]
	s_cbranch_vccz .Lrw_p_skip
	s_setprio 1

; #define LAS __attribute__((address_space(3)))
; __device__ __forceinline__ unsigned pk2(float lo, float hi) { const bf2_t r = __builtin_convertvector((f32x2){lo, hi}, bf2_t); unsigned u; __builtin_memcpy(&u, &r, 4); return u; }
; __device__ __forceinline__ void rwkv_chunk_item(const P& p, const Ctx& c, int seg, int w, bool save) {
;     ...
;         if (c.wv == 0) {
;             float u[16];
; #pragma unroll
;             for (int p2 = 0; p2 < 8; ++p2) { f32x2 acc = (f32x2){XF[c.lane * 17 + 2 * p2], XF[c.lane * 17 + 2 * p2 + 1]};
; #pragma unroll
;                 for (int s2 = 0; s2 < 2 * p2; ++s2) { const f32x2 m = *(const LAS f32x2*)(MABT + s2 * 20 + 2 * p2); acc += (f32x2){u[s2], u[s2]} * m; }
;                 u[2 * p2] = acc.x;
;                 u[2 * p2 + 1] = acc.y + acc.x * MABT[(2 * p2) * 20 + 2 * p2 + 1]; }
;             *(LAS u32x4*)(UV + c.lane * 40) = (u32x4){pk2(u[0], u[1]), pk2(u[2], u[3]), pk2(u[4], u[5]), pk2(u[6], u[7])};
;             *(LAS u32x4*)(UV + c.lane * 40 + 8) = (u32x4){pk2(u[8], u[9]), pk2(u[10], u[11]), pk2(u[12], u[13]), pk2(u[14], u[15])};
;         }
.LBB0_895:
	s_waitcnt lgkmcnt(7)
	v_fma_f32 v46, v170, v100, v101
	v_pk_fma_f32 v[102:103], v[100:101], v[156:157], v[102:103] op_sel_hi:[0,1,1]
	v_pk_fma_f32 v[52:53], v[100:101], v[230:231], v[52:53] op_sel_hi:[0,1,1]
	v_pk_fma_f32 v[56:57], v[100:101], v[232:233], v[56:57] op_sel_hi:[0,1,1]
	v_pk_fma_f32 v[60:61], v[100:101], v[124:125], v[60:61] op_sel_hi:[0,1,1]
	v_pk_fma_f32 v[64:65], v[100:101], v[126:127], v[64:65] op_sel_hi:[0,1,1]
	v_pk_fma_f32 v[68:69], v[100:101], v[176:177], v[68:69] op_sel_hi:[0,1,1]
	v_pk_fma_f32 v[72:73], v[100:101], v[178:179], v[72:73] op_sel_hi:[0,1,1]
	v_pk_fma_f32 v[102:103], v[46:47], v[158:159], v[102:103] op_sel_hi:[0,1,1]
	v_pk_fma_f32 v[52:53], v[46:47], v[234:235], v[52:53] op_sel_hi:[0,1,1]
	v_pk_fma_f32 v[56:57], v[46:47], v[236:237], v[56:57] op_sel_hi:[0,1,1]
	v_pk_fma_f32 v[60:61], v[46:47], v[128:129], v[60:61] op_sel_hi:[0,1,1]
	v_pk_fma_f32 v[64:65], v[46:47], v[130:131], v[64:65] op_sel_hi:[0,1,1]
	v_pk_fma_f32 v[68:69], v[46:47], v[180:181], v[68:69] op_sel_hi:[0,1,1]
	v_pk_fma_f32 v[72:73], v[46:47], v[182:183], v[72:73] op_sel_hi:[0,1,1]
	ds_read_b32 v173, v253 offset:22356
	ds_read_b64 v[160:161], v253 offset:22360
	ds_read_b128 v[140:143], v253 offset:22368
	ds_read_b128 v[192:195], v253 offset:22384
	ds_read_b64 v[162:163], v253 offset:22440
	ds_read_b128 v[144:147], v253 offset:22448
	ds_read_b128 v[196:199], v253 offset:22464
	s_waitcnt lgkmcnt(7)
	v_fma_f32 v50, v172, v102, v103
	v_pk_fma_f32 v[52:53], v[102:103], v[238:239], v[52:53] op_sel_hi:[0,1,1]
	v_pk_fma_f32 v[56:57], v[102:103], v[240:241], v[56:57] op_sel_hi:[0,1,1]
	v_pk_fma_f32 v[60:61], v[102:103], v[132:133], v[60:61] op_sel_hi:[0,1,1]
	v_pk_fma_f32 v[64:65], v[102:103], v[134:135], v[64:65] op_sel_hi:[0,1,1]
	v_pk_fma_f32 v[68:69], v[102:103], v[184:185], v[68:69] op_sel_hi:[0,1,1]
	v_pk_fma_f32 v[72:73], v[102:103], v[186:187], v[72:73] op_sel_hi:[0,1,1]
	v_pk_fma_f32 v[52:53], v[50:51], v[242:243], v[52:53] op_sel_hi:[0,1,1]
	v_pk_fma_f32 v[56:57], v[50:51], v[244:245], v[56:57] op_sel_hi:[0,1,1]
	v_pk_fma_f32 v[60:61], v[50:51], v[136:137], v[60:61] op_sel_hi:[0,1,1]
	v_pk_fma_f32 v[64:65], v[50:51], v[138:139], v[64:65] op_sel_hi:[0,1,1]
	v_pk_fma_f32 v[68:69], v[50:51], v[188:189], v[68:69] op_sel_hi:[0,1,1]
	v_pk_fma_f32 v[72:73], v[50:51], v[190:191], v[72:73] op_sel_hi:[0,1,1]
	ds_read_b32 v174, v253 offset:22524
	ds_read_b128 v[148:151], v253 offset:22528
	ds_read_b128 v[200:203], v253 offset:22544
	ds_read_b128 v[152:155], v253 offset:22608
	ds_read_b128 v[204:207], v253 offset:22624
	s_waitcnt lgkmcnt(5)
	v_fma_f32 v54, v173, v52, v53
	v_pk_fma_f32 v[56:57], v[52:53], v[160:161], v[56:57] op_sel_hi:[0,1,1]
	v_pk_fma_f32 v[60:61], v[52:53], v[140:141], v[60:61] op_sel_hi:[0,1,1]
	v_pk_fma_f32 v[64:65], v[52:53], v[142:143], v[64:65] op_sel_hi:[0,1,1]
	v_pk_fma_f32 v[68:69], v[52:53], v[192:193], v[68:69] op_sel_hi:[0,1,1]
	v_pk_fma_f32 v[72:73], v[52:53], v[194:195], v[72:73] op_sel_hi:[0,1,1]
	v_pk_fma_f32 v[56:57], v[54:55], v[162:163], v[56:57] op_sel_hi:[0,1,1]
	v_pk_fma_f32 v[60:61], v[54:55], v[144:145], v[60:61] op_sel_hi:[0,1,1]
	v_pk_fma_f32 v[64:65], v[54:55], v[146:147], v[64:65] op_sel_hi:[0,1,1]
	v_pk_fma_f32 v[68:69], v[54:55], v[196:197], v[68:69] op_sel_hi:[0,1,1]
	v_pk_fma_f32 v[72:73], v[54:55], v[198:199], v[72:73] op_sel_hi:[0,1,1]
	ds_read_b32 v248, v253 offset:22692
	ds_read_b64 v[164:165], v253 offset:22696
	ds_read_b128 v[208:211], v253 offset:22704
	ds_read_b64 v[166:167], v253 offset:22776
	ds_read_b128 v[218:221], v253 offset:22784
	s_waitcnt lgkmcnt(5)
	v_fma_f32 v58, v174, v56, v57
	v_pk_fma_f32 v[60:61], v[56:57], v[148:149], v[60:61] op_sel_hi:[0,1,1]
	v_pk_fma_f32 v[64:65], v[56:57], v[150:151], v[64:65] op_sel_hi:[0,1,1]
	v_pk_fma_f32 v[68:69], v[56:57], v[200:201], v[68:69] op_sel_hi:[0,1,1]
	v_pk_fma_f32 v[72:73], v[56:57], v[202:203], v[72:73] op_sel_hi:[0,1,1]
	v_pk_fma_f32 v[60:61], v[58:59], v[152:153], v[60:61] op_sel_hi:[0,1,1]
	v_pk_fma_f32 v[64:65], v[58:59], v[154:155], v[64:65] op_sel_hi:[0,1,1]
	v_pk_fma_f32 v[68:69], v[58:59], v[204:205], v[68:69] op_sel_hi:[0,1,1]
	v_pk_fma_f32 v[72:73], v[58:59], v[206:207], v[72:73] op_sel_hi:[0,1,1]
	ds_read_b32 v249, v253 offset:22860
	ds_read_b128 v[222:225], v253 offset:22864
	ds_read_b128 v[226:229], v253 offset:22944
	s_waitcnt lgkmcnt(3)
	v_fma_f32 v62, v248, v60, v61
	v_pk_fma_f32 v[64:65], v[60:61], v[164:165], v[64:65] op_sel_hi:[0,1,1]
	v_pk_fma_f32 v[68:69], v[60:61], v[208:209], v[68:69] op_sel_hi:[0,1,1]
	v_pk_fma_f32 v[72:73], v[60:61], v[210:211], v[72:73] op_sel_hi:[0,1,1]
	v_pk_fma_f32 v[64:65], v[62:63], v[166:167], v[64:65] op_sel_hi:[0,1,1]
	v_pk_fma_f32 v[68:69], v[62:63], v[218:219], v[68:69] op_sel_hi:[0,1,1]
	v_pk_fma_f32 v[72:73], v[62:63], v[220:221], v[72:73] op_sel_hi:[0,1,1]
	ds_read_b32 v250, v253 offset:23028
	ds_read_b64 v[168:169], v253 offset:23032
	ds_read_b64 v[246:247], v253 offset:23112
	s_waitcnt lgkmcnt(3)
	v_fma_f32 v66, v249, v64, v65
	v_pk_fma_f32 v[68:69], v[64:65], v[222:223], v[68:69] op_sel_hi:[0,1,1]
	v_pk_fma_f32 v[72:73], v[64:65], v[224:225], v[72:73] op_sel_hi:[0,1,1]
	v_pk_fma_f32 v[68:69], v[66:67], v[226:227], v[68:69] op_sel_hi:[0,1,1]
	v_pk_fma_f32 v[72:73], v[66:67], v[228:229], v[72:73] op_sel_hi:[0,1,1]
	ds_read_b32 v251, v253 offset:23196
	s_waitcnt lgkmcnt(1)
	v_fma_f32 v120, v250, v68, v69
	v_pk_fma_f32 v[72:73], v[68:69], v[168:169], v[72:73] op_sel_hi:[0,1,1]
	v_pk_fma_f32 v[72:73], v[120:121], v[246:247], v[72:73] op_sel_hi:[0,1,1]
	s_waitcnt lgkmcnt(0)
	v_fma_f32 v122, v251, v72, v73
	v_add_u32_e32 v252, s88, v80
	v_cvt_pk_bf16_f32 v44, v100, v46
	v_cvt_pk_bf16_f32 v45, v102, v50
	v_cvt_pk_bf16_f32 v46, v52, v54
	v_cvt_pk_bf16_f32 v47, v56, v58
	ds_write_b128 v252, v[44:47] offset:14336
	v_cvt_pk_bf16_f32 v44, v60, v62
	v_cvt_pk_bf16_f32 v45, v64, v66
	v_cvt_pk_bf16_f32 v46, v68, v120
	v_cvt_pk_bf16_f32 v47, v72, v122
	ds_write_b128 v252, v[44:47] offset:14352
	s_setprio 1
